# U loop unrolled x2 (x register copies removed)
# baseline (speedup 1.0000x reference)
; #define PG_ISSUE(BUF, TAB, e0_) do { const int isrc_ = ((e0_) < 64) ? myi0 : myi1; \
;       _Pragma("unroll") for (int e = 0; e < 8; ++e) { const int idx_ = __builtin_amdgcn_readlane(isrc_, ((e0_) + e) & 63); \
;         BUF[e] = *(const u32x4*)((TAB) + (size_t)idx_ * 1024 + lane * 16); } } while (0)
; DEV void peer_gather(const Params& P, int l, int m0, const int* idxs, const float* gs) {
;     ...
;     for (int e0 = 0; e0 < 128; e0 += 16) {
;       PG_ISSUE(b1, U, e0 + 8);
;       PG_U8(b0, 0, e0);
;       if (e0 + 16 < 128) PG_ISSUE(b0, U, e0 + 16); else PG_ISSUE(b0, V, 0);
;       PG_U8(b1, 0, e0 + 8);
.Lpg0_uloop:
	s_and_b32 s98, s100, 15
	s_add_u32 s92, s100, 1
	s_min_u32 s92, s92, 127
	s_lshr_b32 s93, s92, 4
	s_and_b32 s92, s92, 15
	s_waitcnt vmcnt(16) lgkmcnt(0)
	s_lshl3_add_u32 vcc_lo, s92, s93
	v_lshl_add_u32 v119, vcc_lo, 8, v236
	global_load_dwordx4 v[64:67], v119, s[82:83]
	global_load_dwordx4 v[68:71], v119, s[82:83] offset:16
	v_lshl_or_b32 v240, s93, 21, v235
	s_waitcnt vmcnt(16)
	v_cvt_scalef32_pk_bf16_fp8 v104, v0, 1.0
	v_cvt_scalef32_pk_bf16_fp8 v105, v0, 1.0 op_sel:[1,0,0]
	v_cvt_scalef32_pk_bf16_fp8 v106, v4, 1.0
	v_cvt_scalef32_pk_bf16_fp8 v107, v4, 1.0 op_sel:[1,0,0]
	v_cvt_scalef32_pk_bf16_fp8 v108, v1, 1.0
	v_cvt_scalef32_pk_bf16_fp8 v109, v1, 1.0 op_sel:[1,0,0]
	v_mfma_f32_4x4x4_16b_bf16 v[72:75], v[104:105], v[80:81], 0
	v_cvt_scalef32_pk_bf16_fp8 v110, v5, 1.0
	v_cvt_scalef32_pk_bf16_fp8 v111, v5, 1.0 op_sel:[1,0,0]
	v_mfma_f32_4x4x4_16b_bf16 v[76:79], v[106:107], v[80:81], 0
	v_cvt_scalef32_pk_bf16_fp8 v104, v2, 1.0
	v_cvt_scalef32_pk_bf16_fp8 v105, v2, 1.0 op_sel:[1,0,0]
	v_mfma_f32_4x4x4_16b_bf16 v[72:75], v[108:109], v[82:83], v[72:75]
	v_cvt_scalef32_pk_bf16_fp8 v106, v6, 1.0
	v_cvt_scalef32_pk_bf16_fp8 v107, v6, 1.0 op_sel:[1,0,0]
	v_mfma_f32_4x4x4_16b_bf16 v[76:79], v[110:111], v[82:83], v[76:79]
	v_cvt_scalef32_pk_bf16_fp8 v108, v3, 1.0
	v_cvt_scalef32_pk_bf16_fp8 v109, v3, 1.0 op_sel:[1,0,0]
	v_mfma_f32_4x4x4_16b_bf16 v[72:75], v[104:105], v[84:85], v[72:75]
	v_cvt_scalef32_pk_bf16_fp8 v110, v7, 1.0
	v_cvt_scalef32_pk_bf16_fp8 v111, v7, 1.0 op_sel:[1,0,0]
	v_mfma_f32_4x4x4_16b_bf16 v[76:79], v[106:107], v[84:85], v[76:79]
	v_and_or_b32 v112, v112, s2, v240
	v_and_or_b32 v113, v113, s2, v240
	global_load_dwordx4 v[0:3], v112, s[80:81]
	global_load_dwordx4 v[4:7], v113, s[80:81]
	s_waitcnt vmcnt(16)
	v_cvt_scalef32_pk_bf16_fp8 v104, v8, 1.0
	v_cvt_scalef32_pk_bf16_fp8 v105, v8, 1.0 op_sel:[1,0,0]
	v_mfma_f32_4x4x4_16b_bf16 v[72:75], v[108:109], v[86:87], v[72:75]
	v_cvt_scalef32_pk_bf16_fp8 v106, v12, 1.0
	v_cvt_scalef32_pk_bf16_fp8 v107, v12, 1.0 op_sel:[1,0,0]
	v_mfma_f32_4x4x4_16b_bf16 v[76:79], v[110:111], v[86:87], v[76:79]
	v_cvt_scalef32_pk_bf16_fp8 v108, v9, 1.0
	v_cvt_scalef32_pk_bf16_fp8 v109, v9, 1.0 op_sel:[1,0,0]
	v_cvt_scalef32_pk_bf16_fp8 v110, v13, 1.0
	v_cvt_scalef32_pk_bf16_fp8 v111, v13, 1.0 op_sel:[1,0,0]
	v_add_f32_dpp v148, v73, v72 quad_perm:[1,0,3,2] row_mask:0xf bank_mask:0xf
	v_add_f32_dpp v149, v75, v74 quad_perm:[1,0,3,2] row_mask:0xf bank_mask:0xf
	v_add_f32_dpp v150, v76, v77 quad_perm:[1,0,3,2] row_mask:0xf bank_mask:0xf
	v_add_f32_dpp v151, v78, v79 quad_perm:[1,0,3,2] row_mask:0xf bank_mask:0xf
	v_mfma_f32_4x4x4_16b_bf16 v[72:75], v[104:105], v[80:81], 0
	v_add_f32_dpp v88, v149, v148 quad_perm:[2,3,0,1] row_mask:0xf bank_mask:0xf
	v_mfma_f32_4x4x4_16b_bf16 v[76:79], v[106:107], v[80:81], 0
	v_add_f32_dpp v89, v151, v150 quad_perm:[2,3,0,1] row_mask:0xf bank_mask:0xf
	v_cvt_scalef32_pk_bf16_fp8 v104, v10, 1.0
	v_cvt_scalef32_pk_bf16_fp8 v105, v10, 1.0 op_sel:[1,0,0]
	v_mfma_f32_4x4x4_16b_bf16 v[72:75], v[108:109], v[82:83], v[72:75]
	v_cvt_scalef32_pk_bf16_fp8 v106, v14, 1.0
	v_cvt_scalef32_pk_bf16_fp8 v107, v14, 1.0 op_sel:[1,0,0]
	v_mfma_f32_4x4x4_16b_bf16 v[76:79], v[110:111], v[82:83], v[76:79]
	v_cvt_scalef32_pk_bf16_fp8 v108, v11, 1.0
	v_cvt_scalef32_pk_bf16_fp8 v109, v11, 1.0 op_sel:[1,0,0]
	v_mfma_f32_4x4x4_16b_bf16 v[72:75], v[104:105], v[84:85], v[72:75]
	v_cvt_scalef32_pk_bf16_fp8 v110, v15, 1.0
	v_cvt_scalef32_pk_bf16_fp8 v111, v15, 1.0 op_sel:[1,0,0]
	v_mfma_f32_4x4x4_16b_bf16 v[76:79], v[106:107], v[84:85], v[76:79]
	v_and_or_b32 v114, v114, s2, v240
	v_and_or_b32 v115, v115, s2, v240
	global_load_dwordx4 v[8:11], v114, s[80:81]
	global_load_dwordx4 v[12:15], v115, s[80:81]
	s_waitcnt vmcnt(16)
	v_cvt_scalef32_pk_bf16_fp8 v104, v16, 1.0
	v_cvt_scalef32_pk_bf16_fp8 v105, v16, 1.0 op_sel:[1,0,0]
	v_mfma_f32_4x4x4_16b_bf16 v[72:75], v[108:109], v[86:87], v[72:75]
	v_cvt_scalef32_pk_bf16_fp8 v106, v20, 1.0
	v_cvt_scalef32_pk_bf16_fp8 v107, v20, 1.0 op_sel:[1,0,0]
	v_mfma_f32_4x4x4_16b_bf16 v[76:79], v[110:111], v[86:87], v[76:79]
	v_cvt_scalef32_pk_bf16_fp8 v108, v17, 1.0
	v_cvt_scalef32_pk_bf16_fp8 v109, v17, 1.0 op_sel:[1,0,0]
	v_cvt_scalef32_pk_bf16_fp8 v110, v21, 1.0
	v_cvt_scalef32_pk_bf16_fp8 v111, v21, 1.0 op_sel:[1,0,0]
	v_add_f32_dpp v148, v75, v74 quad_perm:[1,0,3,2] row_mask:0xf bank_mask:0xf
	v_add_f32_dpp v149, v73, v72 quad_perm:[1,0,3,2] row_mask:0xf bank_mask:0xf
	v_add_f32_dpp v150, v78, v79 quad_perm:[1,0,3,2] row_mask:0xf bank_mask:0xf
	v_add_f32_dpp v151, v76, v77 quad_perm:[1,0,3,2] row_mask:0xf bank_mask:0xf
	v_mfma_f32_4x4x4_16b_bf16 v[72:75], v[104:105], v[80:81], 0
	v_add_f32_dpp v90, v149, v148 quad_perm:[2,3,0,1] row_mask:0xf bank_mask:0xf
	v_mfma_f32_4x4x4_16b_bf16 v[76:79], v[106:107], v[80:81], 0
	v_add_f32_dpp v91, v151, v150 quad_perm:[2,3,0,1] row_mask:0xf bank_mask:0xf
	v_cvt_scalef32_pk_bf16_fp8 v104, v18, 1.0
	v_cvt_scalef32_pk_bf16_fp8 v105, v18, 1.0 op_sel:[1,0,0]
	v_mfma_f32_4x4x4_16b_bf16 v[72:75], v[108:109], v[82:83], v[72:75]
	v_cvt_scalef32_pk_bf16_fp8 v106, v22, 1.0
	v_cvt_scalef32_pk_bf16_fp8 v107, v22, 1.0 op_sel:[1,0,0]
	v_mfma_f32_4x4x4_16b_bf16 v[76:79], v[110:111], v[82:83], v[76:79]
	v_cvt_scalef32_pk_bf16_fp8 v108, v19, 1.0
	v_cvt_scalef32_pk_bf16_fp8 v109, v19, 1.0 op_sel:[1,0,0]
	v_mfma_f32_4x4x4_16b_bf16 v[72:75], v[104:105], v[84:85], v[72:75]
	v_cvt_scalef32_pk_bf16_fp8 v110, v23, 1.0
	v_cvt_scalef32_pk_bf16_fp8 v111, v23, 1.0 op_sel:[1,0,0]
	v_mfma_f32_4x4x4_16b_bf16 v[76:79], v[106:107], v[84:85], v[76:79]
	v_and_or_b32 v138, v138, s2, v240
	v_and_or_b32 v139, v139, s2, v240
	global_load_dwordx4 v[16:19], v138, s[80:81]
	global_load_dwordx4 v[20:23], v139, s[80:81]
	s_waitcnt vmcnt(16)
; #define PG_ISSUE(BUF, TAB, e0_) do { const int isrc_ = ((e0_) < 64) ? myi0 : myi1; \
;       _Pragma("unroll") for (int e = 0; e < 8; ++e) { const int idx_ = __builtin_amdgcn_readlane(isrc_, ((e0_) + e) & 63); \
;         BUF[e] = *(const u32x4*)((TAB) + (size_t)idx_ * 1024 + lane * 16); } } while (0)
; DEV void peer_gather(const Params& P, int l, int m0, const int* idxs, const float* gs) {
;     ...
;     for (int e0 = 0; e0 < 128; e0 += 16) {
;       PG_ISSUE(b1, U, e0 + 8);
;       PG_U8(b0, 0, e0);
;       if (e0 + 16 < 128) PG_ISSUE(b0, U, e0 + 16); else PG_ISSUE(b0, V, 0);
;       PG_U8(b1, 0, e0 + 8);
	v_cvt_scalef32_pk_bf16_fp8 v104, v24, 1.0
	v_cvt_scalef32_pk_bf16_fp8 v105, v24, 1.0 op_sel:[1,0,0]
	v_mfma_f32_4x4x4_16b_bf16 v[72:75], v[108:109], v[86:87], v[72:75]
	v_cvt_scalef32_pk_bf16_fp8 v106, v28, 1.0
	v_cvt_scalef32_pk_bf16_fp8 v107, v28, 1.0 op_sel:[1,0,0]
	v_mfma_f32_4x4x4_16b_bf16 v[76:79], v[110:111], v[86:87], v[76:79]
	v_cvt_scalef32_pk_bf16_fp8 v108, v25, 1.0
	v_cvt_scalef32_pk_bf16_fp8 v109, v25, 1.0 op_sel:[1,0,0]
	v_cvt_scalef32_pk_bf16_fp8 v110, v29, 1.0
	v_cvt_scalef32_pk_bf16_fp8 v111, v29, 1.0 op_sel:[1,0,0]
	v_add_f32_dpp v148, v73, v72 quad_perm:[1,0,3,2] row_mask:0xf bank_mask:0xf
	v_add_f32_dpp v149, v75, v74 quad_perm:[1,0,3,2] row_mask:0xf bank_mask:0xf
	v_add_f32_dpp v150, v76, v77 quad_perm:[1,0,3,2] row_mask:0xf bank_mask:0xf
	v_add_f32_dpp v151, v78, v79 quad_perm:[1,0,3,2] row_mask:0xf bank_mask:0xf
	v_mfma_f32_4x4x4_16b_bf16 v[72:75], v[104:105], v[80:81], 0
	v_add_f32_dpp v92, v149, v148 quad_perm:[2,3,0,1] row_mask:0xf bank_mask:0xf
	v_mfma_f32_4x4x4_16b_bf16 v[76:79], v[106:107], v[80:81], 0
	v_add_f32_dpp v93, v151, v150 quad_perm:[2,3,0,1] row_mask:0xf bank_mask:0xf
	v_cvt_scalef32_pk_bf16_fp8 v104, v26, 1.0
	v_cvt_scalef32_pk_bf16_fp8 v105, v26, 1.0 op_sel:[1,0,0]
	v_mfma_f32_4x4x4_16b_bf16 v[72:75], v[108:109], v[82:83], v[72:75]
	v_cvt_scalef32_pk_bf16_fp8 v106, v30, 1.0
	v_cvt_scalef32_pk_bf16_fp8 v107, v30, 1.0 op_sel:[1,0,0]
	v_mfma_f32_4x4x4_16b_bf16 v[76:79], v[110:111], v[82:83], v[76:79]
	v_cvt_scalef32_pk_bf16_fp8 v108, v27, 1.0
	v_cvt_scalef32_pk_bf16_fp8 v109, v27, 1.0 op_sel:[1,0,0]
	v_mfma_f32_4x4x4_16b_bf16 v[72:75], v[104:105], v[84:85], v[72:75]
	v_cvt_scalef32_pk_bf16_fp8 v110, v31, 1.0
	v_cvt_scalef32_pk_bf16_fp8 v111, v31, 1.0 op_sel:[1,0,0]
	v_mfma_f32_4x4x4_16b_bf16 v[76:79], v[106:107], v[84:85], v[76:79]
	v_and_or_b32 v140, v140, s2, v240
	v_and_or_b32 v141, v141, s2, v240
	global_load_dwordx4 v[24:27], v140, s[80:81]
	global_load_dwordx4 v[28:31], v141, s[80:81]
	s_waitcnt vmcnt(16)
	v_cvt_scalef32_pk_bf16_fp8 v104, v32, 1.0
	v_cvt_scalef32_pk_bf16_fp8 v105, v32, 1.0 op_sel:[1,0,0]
	v_mfma_f32_4x4x4_16b_bf16 v[72:75], v[108:109], v[86:87], v[72:75]
	v_cvt_scalef32_pk_bf16_fp8 v106, v36, 1.0
	v_cvt_scalef32_pk_bf16_fp8 v107, v36, 1.0 op_sel:[1,0,0]
	v_mfma_f32_4x4x4_16b_bf16 v[76:79], v[110:111], v[86:87], v[76:79]
	v_cvt_scalef32_pk_bf16_fp8 v108, v33, 1.0
	v_cvt_scalef32_pk_bf16_fp8 v109, v33, 1.0 op_sel:[1,0,0]
	v_cvt_scalef32_pk_bf16_fp8 v110, v37, 1.0
	v_cvt_scalef32_pk_bf16_fp8 v111, v37, 1.0 op_sel:[1,0,0]
	v_add_f32_dpp v148, v75, v74 quad_perm:[1,0,3,2] row_mask:0xf bank_mask:0xf
	v_add_f32_dpp v149, v73, v72 quad_perm:[1,0,3,2] row_mask:0xf bank_mask:0xf
	v_add_f32_dpp v150, v78, v79 quad_perm:[1,0,3,2] row_mask:0xf bank_mask:0xf
	v_add_f32_dpp v151, v76, v77 quad_perm:[1,0,3,2] row_mask:0xf bank_mask:0xf
	v_mfma_f32_4x4x4_16b_bf16 v[72:75], v[104:105], v[80:81], 0
	v_add_f32_dpp v94, v149, v148 quad_perm:[2,3,0,1] row_mask:0xf bank_mask:0xf
	v_mfma_f32_4x4x4_16b_bf16 v[76:79], v[106:107], v[80:81], 0
	v_add_f32_dpp v95, v151, v150 quad_perm:[2,3,0,1] row_mask:0xf bank_mask:0xf
	v_cvt_scalef32_pk_bf16_fp8 v104, v34, 1.0
	v_cvt_scalef32_pk_bf16_fp8 v105, v34, 1.0 op_sel:[1,0,0]
	v_mfma_f32_4x4x4_16b_bf16 v[72:75], v[108:109], v[82:83], v[72:75]
	v_cvt_scalef32_pk_bf16_fp8 v106, v38, 1.0
	v_cvt_scalef32_pk_bf16_fp8 v107, v38, 1.0 op_sel:[1,0,0]
	v_mfma_f32_4x4x4_16b_bf16 v[76:79], v[110:111], v[82:83], v[76:79]
	v_cvt_scalef32_pk_bf16_fp8 v108, v35, 1.0
	v_cvt_scalef32_pk_bf16_fp8 v109, v35, 1.0 op_sel:[1,0,0]
	v_mfma_f32_4x4x4_16b_bf16 v[72:75], v[104:105], v[84:85], v[72:75]
	v_cvt_scalef32_pk_bf16_fp8 v110, v39, 1.0
	v_cvt_scalef32_pk_bf16_fp8 v111, v39, 1.0 op_sel:[1,0,0]
	v_mfma_f32_4x4x4_16b_bf16 v[76:79], v[106:107], v[84:85], v[76:79]
	v_and_or_b32 v250, v250, s2, v240
	v_and_or_b32 v251, v251, s2, v240
	global_load_dwordx4 v[32:35], v250, s[80:81]
	global_load_dwordx4 v[36:39], v251, s[80:81]
	s_waitcnt vmcnt(16)
	v_cvt_scalef32_pk_bf16_fp8 v104, v40, 1.0
	v_cvt_scalef32_pk_bf16_fp8 v105, v40, 1.0 op_sel:[1,0,0]
	v_mfma_f32_4x4x4_16b_bf16 v[72:75], v[108:109], v[86:87], v[72:75]
	v_cvt_scalef32_pk_bf16_fp8 v106, v44, 1.0
	v_cvt_scalef32_pk_bf16_fp8 v107, v44, 1.0 op_sel:[1,0,0]
	v_mfma_f32_4x4x4_16b_bf16 v[76:79], v[110:111], v[86:87], v[76:79]
	v_cvt_scalef32_pk_bf16_fp8 v108, v41, 1.0
	v_cvt_scalef32_pk_bf16_fp8 v109, v41, 1.0 op_sel:[1,0,0]
	v_cvt_scalef32_pk_bf16_fp8 v110, v45, 1.0
	v_cvt_scalef32_pk_bf16_fp8 v111, v45, 1.0 op_sel:[1,0,0]
	v_add_f32_dpp v148, v73, v72 quad_perm:[1,0,3,2] row_mask:0xf bank_mask:0xf
	v_add_f32_dpp v149, v75, v74 quad_perm:[1,0,3,2] row_mask:0xf bank_mask:0xf
	v_add_f32_dpp v150, v76, v77 quad_perm:[1,0,3,2] row_mask:0xf bank_mask:0xf
	v_add_f32_dpp v151, v78, v79 quad_perm:[1,0,3,2] row_mask:0xf bank_mask:0xf
	v_mfma_f32_4x4x4_16b_bf16 v[72:75], v[104:105], v[80:81], 0
	v_add_f32_dpp v96, v149, v148 quad_perm:[2,3,0,1] row_mask:0xf bank_mask:0xf
	v_mfma_f32_4x4x4_16b_bf16 v[76:79], v[106:107], v[80:81], 0
	v_add_f32_dpp v97, v151, v150 quad_perm:[2,3,0,1] row_mask:0xf bank_mask:0xf
	v_cvt_scalef32_pk_bf16_fp8 v104, v42, 1.0
	v_cvt_scalef32_pk_bf16_fp8 v105, v42, 1.0 op_sel:[1,0,0]
	v_mfma_f32_4x4x4_16b_bf16 v[72:75], v[108:109], v[82:83], v[72:75]
	v_cvt_scalef32_pk_bf16_fp8 v106, v46, 1.0
	v_cvt_scalef32_pk_bf16_fp8 v107, v46, 1.0 op_sel:[1,0,0]
	v_mfma_f32_4x4x4_16b_bf16 v[76:79], v[110:111], v[82:83], v[76:79]
	v_cvt_scalef32_pk_bf16_fp8 v108, v43, 1.0
	v_cvt_scalef32_pk_bf16_fp8 v109, v43, 1.0 op_sel:[1,0,0]
	v_mfma_f32_4x4x4_16b_bf16 v[72:75], v[104:105], v[84:85], v[72:75]
	v_cvt_scalef32_pk_bf16_fp8 v110, v47, 1.0
	v_cvt_scalef32_pk_bf16_fp8 v111, v47, 1.0 op_sel:[1,0,0]
	v_mfma_f32_4x4x4_16b_bf16 v[76:79], v[106:107], v[84:85], v[76:79]
	v_and_or_b32 v252, v252, s2, v240
	v_and_or_b32 v253, v253, s2, v240
	global_load_dwordx4 v[40:43], v252, s[80:81]
	global_load_dwordx4 v[44:47], v253, s[80:81]
	s_waitcnt vmcnt(16)
; #define PG_ISSUE(BUF, TAB, e0_) do { const int isrc_ = ((e0_) < 64) ? myi0 : myi1; \
;       _Pragma("unroll") for (int e = 0; e < 8; ++e) { const int idx_ = __builtin_amdgcn_readlane(isrc_, ((e0_) + e) & 63); \
;         BUF[e] = *(const u32x4*)((TAB) + (size_t)idx_ * 1024 + lane * 16); } } while (0)
; DEV void peer_gather(const Params& P, int l, int m0, const int* idxs, const float* gs) {
;     ...
;     for (int e0 = 0; e0 < 128; e0 += 16) {
;       PG_ISSUE(b1, U, e0 + 8);
;       PG_U8(b0, 0, e0);
;       if (e0 + 16 < 128) PG_ISSUE(b0, U, e0 + 16); else PG_ISSUE(b0, V, 0);
;       PG_U8(b1, 0, e0 + 8);
	v_cvt_scalef32_pk_bf16_fp8 v104, v48, 1.0
	v_cvt_scalef32_pk_bf16_fp8 v105, v48, 1.0 op_sel:[1,0,0]
	v_mfma_f32_4x4x4_16b_bf16 v[72:75], v[108:109], v[86:87], v[72:75]
	v_cvt_scalef32_pk_bf16_fp8 v106, v52, 1.0
	v_cvt_scalef32_pk_bf16_fp8 v107, v52, 1.0 op_sel:[1,0,0]
	v_mfma_f32_4x4x4_16b_bf16 v[76:79], v[110:111], v[86:87], v[76:79]
	v_cvt_scalef32_pk_bf16_fp8 v108, v49, 1.0
	v_cvt_scalef32_pk_bf16_fp8 v109, v49, 1.0 op_sel:[1,0,0]
	v_cvt_scalef32_pk_bf16_fp8 v110, v53, 1.0
	v_cvt_scalef32_pk_bf16_fp8 v111, v53, 1.0 op_sel:[1,0,0]
	v_add_f32_dpp v148, v75, v74 quad_perm:[1,0,3,2] row_mask:0xf bank_mask:0xf
	v_add_f32_dpp v149, v73, v72 quad_perm:[1,0,3,2] row_mask:0xf bank_mask:0xf
	v_add_f32_dpp v150, v78, v79 quad_perm:[1,0,3,2] row_mask:0xf bank_mask:0xf
	v_add_f32_dpp v151, v76, v77 quad_perm:[1,0,3,2] row_mask:0xf bank_mask:0xf
	v_mfma_f32_4x4x4_16b_bf16 v[72:75], v[104:105], v[80:81], 0
	v_add_f32_dpp v98, v149, v148 quad_perm:[2,3,0,1] row_mask:0xf bank_mask:0xf
	v_mfma_f32_4x4x4_16b_bf16 v[76:79], v[106:107], v[80:81], 0
	v_add_f32_dpp v99, v151, v150 quad_perm:[2,3,0,1] row_mask:0xf bank_mask:0xf
	v_cvt_scalef32_pk_bf16_fp8 v104, v50, 1.0
	v_cvt_scalef32_pk_bf16_fp8 v105, v50, 1.0 op_sel:[1,0,0]
	v_mfma_f32_4x4x4_16b_bf16 v[72:75], v[108:109], v[82:83], v[72:75]
	v_cvt_scalef32_pk_bf16_fp8 v106, v54, 1.0
	v_cvt_scalef32_pk_bf16_fp8 v107, v54, 1.0 op_sel:[1,0,0]
	v_mfma_f32_4x4x4_16b_bf16 v[76:79], v[110:111], v[82:83], v[76:79]
	v_cvt_scalef32_pk_bf16_fp8 v108, v51, 1.0
	v_cvt_scalef32_pk_bf16_fp8 v109, v51, 1.0 op_sel:[1,0,0]
	v_mfma_f32_4x4x4_16b_bf16 v[72:75], v[104:105], v[84:85], v[72:75]
	v_cvt_scalef32_pk_bf16_fp8 v110, v55, 1.0
	v_cvt_scalef32_pk_bf16_fp8 v111, v55, 1.0 op_sel:[1,0,0]
	v_mfma_f32_4x4x4_16b_bf16 v[76:79], v[106:107], v[84:85], v[76:79]
	v_and_or_b32 v242, v242, s2, v240
	v_and_or_b32 v243, v243, s2, v240
	global_load_dwordx4 v[48:51], v242, s[80:81]
	global_load_dwordx4 v[52:55], v243, s[80:81]
	s_waitcnt vmcnt(16)
	v_cvt_scalef32_pk_bf16_fp8 v104, v56, 1.0
	v_cvt_scalef32_pk_bf16_fp8 v105, v56, 1.0 op_sel:[1,0,0]
	v_mfma_f32_4x4x4_16b_bf16 v[72:75], v[108:109], v[86:87], v[72:75]
	v_cvt_scalef32_pk_bf16_fp8 v106, v60, 1.0
	v_cvt_scalef32_pk_bf16_fp8 v107, v60, 1.0 op_sel:[1,0,0]
	v_mfma_f32_4x4x4_16b_bf16 v[76:79], v[110:111], v[86:87], v[76:79]
	v_cvt_scalef32_pk_bf16_fp8 v108, v57, 1.0
	v_cvt_scalef32_pk_bf16_fp8 v109, v57, 1.0 op_sel:[1,0,0]
	v_cvt_scalef32_pk_bf16_fp8 v110, v61, 1.0
	v_cvt_scalef32_pk_bf16_fp8 v111, v61, 1.0 op_sel:[1,0,0]
	v_add_f32_dpp v148, v73, v72 quad_perm:[1,0,3,2] row_mask:0xf bank_mask:0xf
	v_add_f32_dpp v149, v75, v74 quad_perm:[1,0,3,2] row_mask:0xf bank_mask:0xf
	v_add_f32_dpp v150, v76, v77 quad_perm:[1,0,3,2] row_mask:0xf bank_mask:0xf
	v_add_f32_dpp v151, v78, v79 quad_perm:[1,0,3,2] row_mask:0xf bank_mask:0xf
	v_mfma_f32_4x4x4_16b_bf16 v[72:75], v[104:105], v[80:81], 0
	v_add_f32_dpp v100, v149, v148 quad_perm:[2,3,0,1] row_mask:0xf bank_mask:0xf
	v_mfma_f32_4x4x4_16b_bf16 v[76:79], v[106:107], v[80:81], 0
	v_add_f32_dpp v101, v151, v150 quad_perm:[2,3,0,1] row_mask:0xf bank_mask:0xf
	v_cvt_scalef32_pk_bf16_fp8 v104, v58, 1.0
	v_cvt_scalef32_pk_bf16_fp8 v105, v58, 1.0 op_sel:[1,0,0]
	v_mfma_f32_4x4x4_16b_bf16 v[72:75], v[108:109], v[82:83], v[72:75]
	v_cvt_scalef32_pk_bf16_fp8 v106, v62, 1.0
	v_cvt_scalef32_pk_bf16_fp8 v107, v62, 1.0 op_sel:[1,0,0]
	v_mfma_f32_4x4x4_16b_bf16 v[76:79], v[110:111], v[82:83], v[76:79]
	v_cvt_scalef32_pk_bf16_fp8 v108, v59, 1.0
	v_cvt_scalef32_pk_bf16_fp8 v109, v59, 1.0 op_sel:[1,0,0]
	v_mfma_f32_4x4x4_16b_bf16 v[72:75], v[104:105], v[84:85], v[72:75]
	v_cvt_scalef32_pk_bf16_fp8 v110, v63, 1.0
	v_cvt_scalef32_pk_bf16_fp8 v111, v63, 1.0 op_sel:[1,0,0]
	v_mfma_f32_4x4x4_16b_bf16 v[76:79], v[106:107], v[84:85], v[76:79]
	v_and_or_b32 v244, v244, s2, v240
	v_and_or_b32 v245, v245, s2, v240
	global_load_dwordx4 v[56:59], v244, s[80:81]
	global_load_dwordx4 v[60:63], v245, s[80:81]
	v_mfma_f32_4x4x4_16b_bf16 v[72:75], v[108:109], v[86:87], v[72:75]
	v_mfma_f32_4x4x4_16b_bf16 v[76:79], v[110:111], v[86:87], v[76:79]
	s_add_u32 s92, s100, 2
	s_and_b32 s92, s92, 15
	v_lshl_add_u32 v116, s92, 9, v246
	ds_read_b128 v[112:115], v116
	ds_read_b128 v[138:141], v116 offset:16
	ds_read_b128 v[250:253], v116 offset:32
	ds_read_b128 v[242:245], v116 offset:48
	v_lshl_add_u32 v117, s98, 9, v247
	ds_read_b32 v136, v117
	ds_read_b32 v137, v117 offset:32
	v_add_f32_dpp v148, v75, v74 quad_perm:[1,0,3,2] row_mask:0xf bank_mask:0xf
	v_add_f32_dpp v149, v73, v72 quad_perm:[1,0,3,2] row_mask:0xf bank_mask:0xf
	v_add_f32_dpp v150, v78, v79 quad_perm:[1,0,3,2] row_mask:0xf bank_mask:0xf
	v_add_f32_dpp v151, v76, v77 quad_perm:[1,0,3,2] row_mask:0xf bank_mask:0xf
	v_add_f32_dpp v102, v149, v148 quad_perm:[2,3,0,1] row_mask:0xf bank_mask:0xf
	s_nop 0
	v_add_f32_dpp v103, v151, v150 quad_perm:[2,3,0,1] row_mask:0xf bank_mask:0xf
	v_cndmask_b32_e64 v144, v88, v89, s[88:89]
	v_cndmask_b32_e64 v145, v90, v91, s[88:89]
	v_cndmask_b32_e64 v88, v144, v145, s[86:87]
	v_cndmask_b32_e64 v144, v92, v93, s[88:89]
	v_cndmask_b32_e64 v145, v94, v95, s[88:89]
	v_cndmask_b32_e64 v92, v144, v145, s[86:87]
	v_cndmask_b32_e64 v144, v96, v97, s[88:89]
	v_cndmask_b32_e64 v145, v98, v99, s[88:89]
	v_cndmask_b32_e64 v96, v144, v145, s[86:87]
	v_cndmask_b32_e64 v144, v100, v101, s[88:89]
	v_cndmask_b32_e64 v145, v102, v103, s[88:89]
	v_cndmask_b32_e64 v100, v144, v145, s[86:87]
	v_cndmask_b32_e64 v144, v88, v92, s[90:91]
	v_cndmask_b32_e64 v145, v92, v88, s[90:91]
	v_cndmask_b32_e64 v146, v96, v100, s[90:91]
	v_cndmask_b32_e64 v147, v100, v96, s[90:91]
	s_nop 1
	v_add_f32_dpp v88, v145, v144 row_shl:4 row_mask:0xf bank_mask:0x5
	v_add_f32_dpp v88, v145, v144 row_shr:4 row_mask:0xf bank_mask:0xa
	v_add_f32_dpp v96, v147, v146 row_shl:4 row_mask:0xf bank_mask:0x5
	v_add_f32_dpp v96, v147, v146 row_shr:4 row_mask:0xf bank_mask:0xa
	s_waitcnt lgkmcnt(0)
; #define PG_ISSUE(BUF, TAB, e0_) do { const int isrc_ = ((e0_) < 64) ? myi0 : myi1; \
;       _Pragma("unroll") for (int e = 0; e < 8; ++e) { const int idx_ = __builtin_amdgcn_readlane(isrc_, ((e0_) + e) & 63); \
;         BUF[e] = *(const u32x4*)((TAB) + (size_t)idx_ * 1024 + lane * 16); } } while (0)
; DEV void peer_gather(const Params& P, int l, int m0, const int* idxs, const float* gs) {
;     ...
;     for (int e0 = 0; e0 < 128; e0 += 16) {
;       PG_ISSUE(b1, U, e0 + 8);
;       PG_U8(b0, 0, e0);
;       if (e0 + 16 < 128) PG_ISSUE(b0, U, e0 + 16); else PG_ISSUE(b0, V, 0);
;       PG_U8(b1, 0, e0 + 8);
	v_add_f32_e32 v136, v136, v88
	v_add_f32_e32 v137, v137, v96
	ds_write_b32 v117, v136
	ds_write_b32 v117, v137 offset:32
	s_add_u32 s100, s100, 1
	s_and_b32 s98, s100, 15
	s_add_u32 s92, s100, 1
	s_min_u32 s92, s92, 127
	s_lshr_b32 s93, s92, 4
	s_and_b32 s92, s92, 15
	s_waitcnt vmcnt(16) lgkmcnt(0)
	s_lshl3_add_u32 vcc_lo, s92, s93
	v_lshl_add_u32 v119, vcc_lo, 8, v236
	global_load_dwordx4 v[80:83], v119, s[82:83]
	global_load_dwordx4 v[84:87], v119, s[82:83] offset:16
	v_lshl_or_b32 v240, s93, 21, v235
	s_waitcnt vmcnt(16)
	v_cvt_scalef32_pk_bf16_fp8 v104, v0, 1.0
	v_cvt_scalef32_pk_bf16_fp8 v105, v0, 1.0 op_sel:[1,0,0]
	v_cvt_scalef32_pk_bf16_fp8 v106, v4, 1.0
	v_cvt_scalef32_pk_bf16_fp8 v107, v4, 1.0 op_sel:[1,0,0]
	v_cvt_scalef32_pk_bf16_fp8 v108, v1, 1.0
	v_cvt_scalef32_pk_bf16_fp8 v109, v1, 1.0 op_sel:[1,0,0]
	v_mfma_f32_4x4x4_16b_bf16 v[72:75], v[104:105], v[64:65], 0
	v_cvt_scalef32_pk_bf16_fp8 v110, v5, 1.0
	v_cvt_scalef32_pk_bf16_fp8 v111, v5, 1.0 op_sel:[1,0,0]
	v_mfma_f32_4x4x4_16b_bf16 v[76:79], v[106:107], v[64:65], 0
	v_cvt_scalef32_pk_bf16_fp8 v104, v2, 1.0
	v_cvt_scalef32_pk_bf16_fp8 v105, v2, 1.0 op_sel:[1,0,0]
	v_mfma_f32_4x4x4_16b_bf16 v[72:75], v[108:109], v[66:67], v[72:75]
	v_cvt_scalef32_pk_bf16_fp8 v106, v6, 1.0
	v_cvt_scalef32_pk_bf16_fp8 v107, v6, 1.0 op_sel:[1,0,0]
	v_mfma_f32_4x4x4_16b_bf16 v[76:79], v[110:111], v[66:67], v[76:79]
	v_cvt_scalef32_pk_bf16_fp8 v108, v3, 1.0
	v_cvt_scalef32_pk_bf16_fp8 v109, v3, 1.0 op_sel:[1,0,0]
	v_mfma_f32_4x4x4_16b_bf16 v[72:75], v[104:105], v[68:69], v[72:75]
	v_cvt_scalef32_pk_bf16_fp8 v110, v7, 1.0
	v_cvt_scalef32_pk_bf16_fp8 v111, v7, 1.0 op_sel:[1,0,0]
	v_mfma_f32_4x4x4_16b_bf16 v[76:79], v[106:107], v[68:69], v[76:79]
	v_and_or_b32 v112, v112, s2, v240
	v_and_or_b32 v113, v113, s2, v240
	global_load_dwordx4 v[0:3], v112, s[80:81]
	global_load_dwordx4 v[4:7], v113, s[80:81]
	s_waitcnt vmcnt(16)
	v_cvt_scalef32_pk_bf16_fp8 v104, v8, 1.0
	v_cvt_scalef32_pk_bf16_fp8 v105, v8, 1.0 op_sel:[1,0,0]
	v_mfma_f32_4x4x4_16b_bf16 v[72:75], v[108:109], v[70:71], v[72:75]
	v_cvt_scalef32_pk_bf16_fp8 v106, v12, 1.0
	v_cvt_scalef32_pk_bf16_fp8 v107, v12, 1.0 op_sel:[1,0,0]
	v_mfma_f32_4x4x4_16b_bf16 v[76:79], v[110:111], v[70:71], v[76:79]
	v_cvt_scalef32_pk_bf16_fp8 v108, v9, 1.0
	v_cvt_scalef32_pk_bf16_fp8 v109, v9, 1.0 op_sel:[1,0,0]
	v_cvt_scalef32_pk_bf16_fp8 v110, v13, 1.0
	v_cvt_scalef32_pk_bf16_fp8 v111, v13, 1.0 op_sel:[1,0,0]
	v_add_f32_dpp v148, v73, v72 quad_perm:[1,0,3,2] row_mask:0xf bank_mask:0xf
	v_add_f32_dpp v149, v75, v74 quad_perm:[1,0,3,2] row_mask:0xf bank_mask:0xf
	v_add_f32_dpp v150, v76, v77 quad_perm:[1,0,3,2] row_mask:0xf bank_mask:0xf
	v_add_f32_dpp v151, v78, v79 quad_perm:[1,0,3,2] row_mask:0xf bank_mask:0xf
	v_mfma_f32_4x4x4_16b_bf16 v[72:75], v[104:105], v[64:65], 0
	v_add_f32_dpp v88, v149, v148 quad_perm:[2,3,0,1] row_mask:0xf bank_mask:0xf
	v_mfma_f32_4x4x4_16b_bf16 v[76:79], v[106:107], v[64:65], 0
	v_add_f32_dpp v89, v151, v150 quad_perm:[2,3,0,1] row_mask:0xf bank_mask:0xf
	v_cvt_scalef32_pk_bf16_fp8 v104, v10, 1.0
	v_cvt_scalef32_pk_bf16_fp8 v105, v10, 1.0 op_sel:[1,0,0]
	v_mfma_f32_4x4x4_16b_bf16 v[72:75], v[108:109], v[66:67], v[72:75]
	v_cvt_scalef32_pk_bf16_fp8 v106, v14, 1.0
	v_cvt_scalef32_pk_bf16_fp8 v107, v14, 1.0 op_sel:[1,0,0]
	v_mfma_f32_4x4x4_16b_bf16 v[76:79], v[110:111], v[66:67], v[76:79]
	v_cvt_scalef32_pk_bf16_fp8 v108, v11, 1.0
	v_cvt_scalef32_pk_bf16_fp8 v109, v11, 1.0 op_sel:[1,0,0]
	v_mfma_f32_4x4x4_16b_bf16 v[72:75], v[104:105], v[68:69], v[72:75]
	v_cvt_scalef32_pk_bf16_fp8 v110, v15, 1.0
	v_cvt_scalef32_pk_bf16_fp8 v111, v15, 1.0 op_sel:[1,0,0]
	v_mfma_f32_4x4x4_16b_bf16 v[76:79], v[106:107], v[68:69], v[76:79]
	v_and_or_b32 v114, v114, s2, v240
	v_and_or_b32 v115, v115, s2, v240
	global_load_dwordx4 v[8:11], v114, s[80:81]
	global_load_dwordx4 v[12:15], v115, s[80:81]
	s_waitcnt vmcnt(16)
	v_cvt_scalef32_pk_bf16_fp8 v104, v16, 1.0
	v_cvt_scalef32_pk_bf16_fp8 v105, v16, 1.0 op_sel:[1,0,0]
	v_mfma_f32_4x4x4_16b_bf16 v[72:75], v[108:109], v[70:71], v[72:75]
	v_cvt_scalef32_pk_bf16_fp8 v106, v20, 1.0
	v_cvt_scalef32_pk_bf16_fp8 v107, v20, 1.0 op_sel:[1,0,0]
	v_mfma_f32_4x4x4_16b_bf16 v[76:79], v[110:111], v[70:71], v[76:79]
	v_cvt_scalef32_pk_bf16_fp8 v108, v17, 1.0
	v_cvt_scalef32_pk_bf16_fp8 v109, v17, 1.0 op_sel:[1,0,0]
	v_cvt_scalef32_pk_bf16_fp8 v110, v21, 1.0
	v_cvt_scalef32_pk_bf16_fp8 v111, v21, 1.0 op_sel:[1,0,0]
	v_add_f32_dpp v148, v75, v74 quad_perm:[1,0,3,2] row_mask:0xf bank_mask:0xf
	v_add_f32_dpp v149, v73, v72 quad_perm:[1,0,3,2] row_mask:0xf bank_mask:0xf
	v_add_f32_dpp v150, v78, v79 quad_perm:[1,0,3,2] row_mask:0xf bank_mask:0xf
	v_add_f32_dpp v151, v76, v77 quad_perm:[1,0,3,2] row_mask:0xf bank_mask:0xf
	v_mfma_f32_4x4x4_16b_bf16 v[72:75], v[104:105], v[64:65], 0
	v_add_f32_dpp v90, v149, v148 quad_perm:[2,3,0,1] row_mask:0xf bank_mask:0xf
	v_mfma_f32_4x4x4_16b_bf16 v[76:79], v[106:107], v[64:65], 0
	v_add_f32_dpp v91, v151, v150 quad_perm:[2,3,0,1] row_mask:0xf bank_mask:0xf
	v_cvt_scalef32_pk_bf16_fp8 v104, v18, 1.0
	v_cvt_scalef32_pk_bf16_fp8 v105, v18, 1.0 op_sel:[1,0,0]
	v_mfma_f32_4x4x4_16b_bf16 v[72:75], v[108:109], v[66:67], v[72:75]
	v_cvt_scalef32_pk_bf16_fp8 v106, v22, 1.0
	v_cvt_scalef32_pk_bf16_fp8 v107, v22, 1.0 op_sel:[1,0,0]
	v_mfma_f32_4x4x4_16b_bf16 v[76:79], v[110:111], v[66:67], v[76:79]
	v_cvt_scalef32_pk_bf16_fp8 v108, v19, 1.0
	v_cvt_scalef32_pk_bf16_fp8 v109, v19, 1.0 op_sel:[1,0,0]
	v_mfma_f32_4x4x4_16b_bf16 v[72:75], v[104:105], v[68:69], v[72:75]
	v_cvt_scalef32_pk_bf16_fp8 v110, v23, 1.0
	v_cvt_scalef32_pk_bf16_fp8 v111, v23, 1.0 op_sel:[1,0,0]
	v_mfma_f32_4x4x4_16b_bf16 v[76:79], v[106:107], v[68:69], v[76:79]
	v_and_or_b32 v138, v138, s2, v240
	v_and_or_b32 v139, v139, s2, v240
	global_load_dwordx4 v[16:19], v138, s[80:81]
	global_load_dwordx4 v[20:23], v139, s[80:81]
	s_waitcnt vmcnt(16)
; #define PG_ISSUE(BUF, TAB, e0_) do { const int isrc_ = ((e0_) < 64) ? myi0 : myi1; \
;       _Pragma("unroll") for (int e = 0; e < 8; ++e) { const int idx_ = __builtin_amdgcn_readlane(isrc_, ((e0_) + e) & 63); \
;         BUF[e] = *(const u32x4*)((TAB) + (size_t)idx_ * 1024 + lane * 16); } } while (0)
; DEV void peer_gather(const Params& P, int l, int m0, const int* idxs, const float* gs) {
;     ...
;     for (int e0 = 0; e0 < 128; e0 += 16) {
;       PG_ISSUE(b1, U, e0 + 8);
;       PG_U8(b0, 0, e0);
;       if (e0 + 16 < 128) PG_ISSUE(b0, U, e0 + 16); else PG_ISSUE(b0, V, 0);
;       PG_U8(b1, 0, e0 + 8);
	v_cvt_scalef32_pk_bf16_fp8 v104, v24, 1.0
	v_cvt_scalef32_pk_bf16_fp8 v105, v24, 1.0 op_sel:[1,0,0]
	v_mfma_f32_4x4x4_16b_bf16 v[72:75], v[108:109], v[70:71], v[72:75]
	v_cvt_scalef32_pk_bf16_fp8 v106, v28, 1.0
	v_cvt_scalef32_pk_bf16_fp8 v107, v28, 1.0 op_sel:[1,0,0]
	v_mfma_f32_4x4x4_16b_bf16 v[76:79], v[110:111], v[70:71], v[76:79]
	v_cvt_scalef32_pk_bf16_fp8 v108, v25, 1.0
	v_cvt_scalef32_pk_bf16_fp8 v109, v25, 1.0 op_sel:[1,0,0]
	v_cvt_scalef32_pk_bf16_fp8 v110, v29, 1.0
	v_cvt_scalef32_pk_bf16_fp8 v111, v29, 1.0 op_sel:[1,0,0]
	v_add_f32_dpp v148, v73, v72 quad_perm:[1,0,3,2] row_mask:0xf bank_mask:0xf
	v_add_f32_dpp v149, v75, v74 quad_perm:[1,0,3,2] row_mask:0xf bank_mask:0xf
	v_add_f32_dpp v150, v76, v77 quad_perm:[1,0,3,2] row_mask:0xf bank_mask:0xf
	v_add_f32_dpp v151, v78, v79 quad_perm:[1,0,3,2] row_mask:0xf bank_mask:0xf
	v_mfma_f32_4x4x4_16b_bf16 v[72:75], v[104:105], v[64:65], 0
	v_add_f32_dpp v92, v149, v148 quad_perm:[2,3,0,1] row_mask:0xf bank_mask:0xf
	v_mfma_f32_4x4x4_16b_bf16 v[76:79], v[106:107], v[64:65], 0
	v_add_f32_dpp v93, v151, v150 quad_perm:[2,3,0,1] row_mask:0xf bank_mask:0xf
	v_cvt_scalef32_pk_bf16_fp8 v104, v26, 1.0
	v_cvt_scalef32_pk_bf16_fp8 v105, v26, 1.0 op_sel:[1,0,0]
	v_mfma_f32_4x4x4_16b_bf16 v[72:75], v[108:109], v[66:67], v[72:75]
	v_cvt_scalef32_pk_bf16_fp8 v106, v30, 1.0
	v_cvt_scalef32_pk_bf16_fp8 v107, v30, 1.0 op_sel:[1,0,0]
	v_mfma_f32_4x4x4_16b_bf16 v[76:79], v[110:111], v[66:67], v[76:79]
	v_cvt_scalef32_pk_bf16_fp8 v108, v27, 1.0
	v_cvt_scalef32_pk_bf16_fp8 v109, v27, 1.0 op_sel:[1,0,0]
	v_mfma_f32_4x4x4_16b_bf16 v[72:75], v[104:105], v[68:69], v[72:75]
	v_cvt_scalef32_pk_bf16_fp8 v110, v31, 1.0
	v_cvt_scalef32_pk_bf16_fp8 v111, v31, 1.0 op_sel:[1,0,0]
	v_mfma_f32_4x4x4_16b_bf16 v[76:79], v[106:107], v[68:69], v[76:79]
	v_and_or_b32 v140, v140, s2, v240
	v_and_or_b32 v141, v141, s2, v240
	global_load_dwordx4 v[24:27], v140, s[80:81]
	global_load_dwordx4 v[28:31], v141, s[80:81]
	s_waitcnt vmcnt(16)
	v_cvt_scalef32_pk_bf16_fp8 v104, v32, 1.0
	v_cvt_scalef32_pk_bf16_fp8 v105, v32, 1.0 op_sel:[1,0,0]
	v_mfma_f32_4x4x4_16b_bf16 v[72:75], v[108:109], v[70:71], v[72:75]
	v_cvt_scalef32_pk_bf16_fp8 v106, v36, 1.0
	v_cvt_scalef32_pk_bf16_fp8 v107, v36, 1.0 op_sel:[1,0,0]
	v_mfma_f32_4x4x4_16b_bf16 v[76:79], v[110:111], v[70:71], v[76:79]
	v_cvt_scalef32_pk_bf16_fp8 v108, v33, 1.0
	v_cvt_scalef32_pk_bf16_fp8 v109, v33, 1.0 op_sel:[1,0,0]
	v_cvt_scalef32_pk_bf16_fp8 v110, v37, 1.0
	v_cvt_scalef32_pk_bf16_fp8 v111, v37, 1.0 op_sel:[1,0,0]
	v_add_f32_dpp v148, v75, v74 quad_perm:[1,0,3,2] row_mask:0xf bank_mask:0xf
	v_add_f32_dpp v149, v73, v72 quad_perm:[1,0,3,2] row_mask:0xf bank_mask:0xf
	v_add_f32_dpp v150, v78, v79 quad_perm:[1,0,3,2] row_mask:0xf bank_mask:0xf
	v_add_f32_dpp v151, v76, v77 quad_perm:[1,0,3,2] row_mask:0xf bank_mask:0xf
	v_mfma_f32_4x4x4_16b_bf16 v[72:75], v[104:105], v[64:65], 0
	v_add_f32_dpp v94, v149, v148 quad_perm:[2,3,0,1] row_mask:0xf bank_mask:0xf
	v_mfma_f32_4x4x4_16b_bf16 v[76:79], v[106:107], v[64:65], 0
	v_add_f32_dpp v95, v151, v150 quad_perm:[2,3,0,1] row_mask:0xf bank_mask:0xf
	v_cvt_scalef32_pk_bf16_fp8 v104, v34, 1.0
	v_cvt_scalef32_pk_bf16_fp8 v105, v34, 1.0 op_sel:[1,0,0]
	v_mfma_f32_4x4x4_16b_bf16 v[72:75], v[108:109], v[66:67], v[72:75]
	v_cvt_scalef32_pk_bf16_fp8 v106, v38, 1.0
	v_cvt_scalef32_pk_bf16_fp8 v107, v38, 1.0 op_sel:[1,0,0]
	v_mfma_f32_4x4x4_16b_bf16 v[76:79], v[110:111], v[66:67], v[76:79]
	v_cvt_scalef32_pk_bf16_fp8 v108, v35, 1.0
	v_cvt_scalef32_pk_bf16_fp8 v109, v35, 1.0 op_sel:[1,0,0]
	v_mfma_f32_4x4x4_16b_bf16 v[72:75], v[104:105], v[68:69], v[72:75]
	v_cvt_scalef32_pk_bf16_fp8 v110, v39, 1.0
	v_cvt_scalef32_pk_bf16_fp8 v111, v39, 1.0 op_sel:[1,0,0]
	v_mfma_f32_4x4x4_16b_bf16 v[76:79], v[106:107], v[68:69], v[76:79]
	v_and_or_b32 v250, v250, s2, v240
	v_and_or_b32 v251, v251, s2, v240
	global_load_dwordx4 v[32:35], v250, s[80:81]
	global_load_dwordx4 v[36:39], v251, s[80:81]
	s_waitcnt vmcnt(16)
	v_cvt_scalef32_pk_bf16_fp8 v104, v40, 1.0
	v_cvt_scalef32_pk_bf16_fp8 v105, v40, 1.0 op_sel:[1,0,0]
	v_mfma_f32_4x4x4_16b_bf16 v[72:75], v[108:109], v[70:71], v[72:75]
	v_cvt_scalef32_pk_bf16_fp8 v106, v44, 1.0
	v_cvt_scalef32_pk_bf16_fp8 v107, v44, 1.0 op_sel:[1,0,0]
	v_mfma_f32_4x4x4_16b_bf16 v[76:79], v[110:111], v[70:71], v[76:79]
	v_cvt_scalef32_pk_bf16_fp8 v108, v41, 1.0
	v_cvt_scalef32_pk_bf16_fp8 v109, v41, 1.0 op_sel:[1,0,0]
	v_cvt_scalef32_pk_bf16_fp8 v110, v45, 1.0
	v_cvt_scalef32_pk_bf16_fp8 v111, v45, 1.0 op_sel:[1,0,0]
	v_add_f32_dpp v148, v73, v72 quad_perm:[1,0,3,2] row_mask:0xf bank_mask:0xf
	v_add_f32_dpp v149, v75, v74 quad_perm:[1,0,3,2] row_mask:0xf bank_mask:0xf
	v_add_f32_dpp v150, v76, v77 quad_perm:[1,0,3,2] row_mask:0xf bank_mask:0xf
	v_add_f32_dpp v151, v78, v79 quad_perm:[1,0,3,2] row_mask:0xf bank_mask:0xf
	v_mfma_f32_4x4x4_16b_bf16 v[72:75], v[104:105], v[64:65], 0
	v_add_f32_dpp v96, v149, v148 quad_perm:[2,3,0,1] row_mask:0xf bank_mask:0xf
	v_mfma_f32_4x4x4_16b_bf16 v[76:79], v[106:107], v[64:65], 0
	v_add_f32_dpp v97, v151, v150 quad_perm:[2,3,0,1] row_mask:0xf bank_mask:0xf
	v_cvt_scalef32_pk_bf16_fp8 v104, v42, 1.0
	v_cvt_scalef32_pk_bf16_fp8 v105, v42, 1.0 op_sel:[1,0,0]
	v_mfma_f32_4x4x4_16b_bf16 v[72:75], v[108:109], v[66:67], v[72:75]
	v_cvt_scalef32_pk_bf16_fp8 v106, v46, 1.0
	v_cvt_scalef32_pk_bf16_fp8 v107, v46, 1.0 op_sel:[1,0,0]
	v_mfma_f32_4x4x4_16b_bf16 v[76:79], v[110:111], v[66:67], v[76:79]
	v_cvt_scalef32_pk_bf16_fp8 v108, v43, 1.0
	v_cvt_scalef32_pk_bf16_fp8 v109, v43, 1.0 op_sel:[1,0,0]
	v_mfma_f32_4x4x4_16b_bf16 v[72:75], v[104:105], v[68:69], v[72:75]
	v_cvt_scalef32_pk_bf16_fp8 v110, v47, 1.0
	v_cvt_scalef32_pk_bf16_fp8 v111, v47, 1.0 op_sel:[1,0,0]
	v_mfma_f32_4x4x4_16b_bf16 v[76:79], v[106:107], v[68:69], v[76:79]
	v_and_or_b32 v252, v252, s2, v240
	v_and_or_b32 v253, v253, s2, v240
	global_load_dwordx4 v[40:43], v252, s[80:81]
	global_load_dwordx4 v[44:47], v253, s[80:81]
	s_waitcnt vmcnt(16)
; #define PG_ISSUE(BUF, TAB, e0_) do { const int isrc_ = ((e0_) < 64) ? myi0 : myi1; \
;       _Pragma("unroll") for (int e = 0; e < 8; ++e) { const int idx_ = __builtin_amdgcn_readlane(isrc_, ((e0_) + e) & 63); \
;         BUF[e] = *(const u32x4*)((TAB) + (size_t)idx_ * 1024 + lane * 16); } } while (0)
; DEV void peer_gather(const Params& P, int l, int m0, const int* idxs, const float* gs) {
;     ...
;     for (int e0 = 0; e0 < 128; e0 += 16) {
;       PG_ISSUE(b1, U, e0 + 8);
;       PG_U8(b0, 0, e0);
;       if (e0 + 16 < 128) PG_ISSUE(b0, U, e0 + 16); else PG_ISSUE(b0, V, 0);
;       PG_U8(b1, 0, e0 + 8);
	v_cvt_scalef32_pk_bf16_fp8 v104, v48, 1.0
	v_cvt_scalef32_pk_bf16_fp8 v105, v48, 1.0 op_sel:[1,0,0]
	v_mfma_f32_4x4x4_16b_bf16 v[72:75], v[108:109], v[70:71], v[72:75]
	v_cvt_scalef32_pk_bf16_fp8 v106, v52, 1.0
	v_cvt_scalef32_pk_bf16_fp8 v107, v52, 1.0 op_sel:[1,0,0]
	v_mfma_f32_4x4x4_16b_bf16 v[76:79], v[110:111], v[70:71], v[76:79]
	v_cvt_scalef32_pk_bf16_fp8 v108, v49, 1.0
	v_cvt_scalef32_pk_bf16_fp8 v109, v49, 1.0 op_sel:[1,0,0]
	v_cvt_scalef32_pk_bf16_fp8 v110, v53, 1.0
	v_cvt_scalef32_pk_bf16_fp8 v111, v53, 1.0 op_sel:[1,0,0]
	v_add_f32_dpp v148, v75, v74 quad_perm:[1,0,3,2] row_mask:0xf bank_mask:0xf
	v_add_f32_dpp v149, v73, v72 quad_perm:[1,0,3,2] row_mask:0xf bank_mask:0xf
	v_add_f32_dpp v150, v78, v79 quad_perm:[1,0,3,2] row_mask:0xf bank_mask:0xf
	v_add_f32_dpp v151, v76, v77 quad_perm:[1,0,3,2] row_mask:0xf bank_mask:0xf
	v_mfma_f32_4x4x4_16b_bf16 v[72:75], v[104:105], v[64:65], 0
	v_add_f32_dpp v98, v149, v148 quad_perm:[2,3,0,1] row_mask:0xf bank_mask:0xf
	v_mfma_f32_4x4x4_16b_bf16 v[76:79], v[106:107], v[64:65], 0
	v_add_f32_dpp v99, v151, v150 quad_perm:[2,3,0,1] row_mask:0xf bank_mask:0xf
	v_cvt_scalef32_pk_bf16_fp8 v104, v50, 1.0
	v_cvt_scalef32_pk_bf16_fp8 v105, v50, 1.0 op_sel:[1,0,0]
	v_mfma_f32_4x4x4_16b_bf16 v[72:75], v[108:109], v[66:67], v[72:75]
	v_cvt_scalef32_pk_bf16_fp8 v106, v54, 1.0
	v_cvt_scalef32_pk_bf16_fp8 v107, v54, 1.0 op_sel:[1,0,0]
	v_mfma_f32_4x4x4_16b_bf16 v[76:79], v[110:111], v[66:67], v[76:79]
	v_cvt_scalef32_pk_bf16_fp8 v108, v51, 1.0
	v_cvt_scalef32_pk_bf16_fp8 v109, v51, 1.0 op_sel:[1,0,0]
	v_mfma_f32_4x4x4_16b_bf16 v[72:75], v[104:105], v[68:69], v[72:75]
	v_cvt_scalef32_pk_bf16_fp8 v110, v55, 1.0
	v_cvt_scalef32_pk_bf16_fp8 v111, v55, 1.0 op_sel:[1,0,0]
	v_mfma_f32_4x4x4_16b_bf16 v[76:79], v[106:107], v[68:69], v[76:79]
	v_and_or_b32 v242, v242, s2, v240
	v_and_or_b32 v243, v243, s2, v240
	global_load_dwordx4 v[48:51], v242, s[80:81]
	global_load_dwordx4 v[52:55], v243, s[80:81]
	s_waitcnt vmcnt(16)
	v_cvt_scalef32_pk_bf16_fp8 v104, v56, 1.0
	v_cvt_scalef32_pk_bf16_fp8 v105, v56, 1.0 op_sel:[1,0,0]
	v_mfma_f32_4x4x4_16b_bf16 v[72:75], v[108:109], v[70:71], v[72:75]
	v_cvt_scalef32_pk_bf16_fp8 v106, v60, 1.0
	v_cvt_scalef32_pk_bf16_fp8 v107, v60, 1.0 op_sel:[1,0,0]
	v_mfma_f32_4x4x4_16b_bf16 v[76:79], v[110:111], v[70:71], v[76:79]
	v_cvt_scalef32_pk_bf16_fp8 v108, v57, 1.0
	v_cvt_scalef32_pk_bf16_fp8 v109, v57, 1.0 op_sel:[1,0,0]
	v_cvt_scalef32_pk_bf16_fp8 v110, v61, 1.0
	v_cvt_scalef32_pk_bf16_fp8 v111, v61, 1.0 op_sel:[1,0,0]
	v_add_f32_dpp v148, v73, v72 quad_perm:[1,0,3,2] row_mask:0xf bank_mask:0xf
	v_add_f32_dpp v149, v75, v74 quad_perm:[1,0,3,2] row_mask:0xf bank_mask:0xf
	v_add_f32_dpp v150, v76, v77 quad_perm:[1,0,3,2] row_mask:0xf bank_mask:0xf
	v_add_f32_dpp v151, v78, v79 quad_perm:[1,0,3,2] row_mask:0xf bank_mask:0xf
	v_mfma_f32_4x4x4_16b_bf16 v[72:75], v[104:105], v[64:65], 0
	v_add_f32_dpp v100, v149, v148 quad_perm:[2,3,0,1] row_mask:0xf bank_mask:0xf
	v_mfma_f32_4x4x4_16b_bf16 v[76:79], v[106:107], v[64:65], 0
	v_add_f32_dpp v101, v151, v150 quad_perm:[2,3,0,1] row_mask:0xf bank_mask:0xf
	v_cvt_scalef32_pk_bf16_fp8 v104, v58, 1.0
	v_cvt_scalef32_pk_bf16_fp8 v105, v58, 1.0 op_sel:[1,0,0]
	v_mfma_f32_4x4x4_16b_bf16 v[72:75], v[108:109], v[66:67], v[72:75]
	v_cvt_scalef32_pk_bf16_fp8 v106, v62, 1.0
	v_cvt_scalef32_pk_bf16_fp8 v107, v62, 1.0 op_sel:[1,0,0]
	v_mfma_f32_4x4x4_16b_bf16 v[76:79], v[110:111], v[66:67], v[76:79]
	v_cvt_scalef32_pk_bf16_fp8 v108, v59, 1.0
	v_cvt_scalef32_pk_bf16_fp8 v109, v59, 1.0 op_sel:[1,0,0]
	v_mfma_f32_4x4x4_16b_bf16 v[72:75], v[104:105], v[68:69], v[72:75]
	v_cvt_scalef32_pk_bf16_fp8 v110, v63, 1.0
	v_cvt_scalef32_pk_bf16_fp8 v111, v63, 1.0 op_sel:[1,0,0]
	v_mfma_f32_4x4x4_16b_bf16 v[76:79], v[106:107], v[68:69], v[76:79]
	v_and_or_b32 v244, v244, s2, v240
	v_and_or_b32 v245, v245, s2, v240
	global_load_dwordx4 v[56:59], v244, s[80:81]
	global_load_dwordx4 v[60:63], v245, s[80:81]
	v_mfma_f32_4x4x4_16b_bf16 v[72:75], v[108:109], v[70:71], v[72:75]
	v_mfma_f32_4x4x4_16b_bf16 v[76:79], v[110:111], v[70:71], v[76:79]
	s_add_u32 s92, s100, 2
	s_and_b32 s92, s92, 15
	v_lshl_add_u32 v116, s92, 9, v246
	ds_read_b128 v[112:115], v116
	ds_read_b128 v[138:141], v116 offset:16
	ds_read_b128 v[250:253], v116 offset:32
	ds_read_b128 v[242:245], v116 offset:48
	v_lshl_add_u32 v117, s98, 9, v247
	ds_read_b32 v136, v117
	ds_read_b32 v137, v117 offset:32
	v_add_f32_dpp v148, v75, v74 quad_perm:[1,0,3,2] row_mask:0xf bank_mask:0xf
	v_add_f32_dpp v149, v73, v72 quad_perm:[1,0,3,2] row_mask:0xf bank_mask:0xf
	v_add_f32_dpp v150, v78, v79 quad_perm:[1,0,3,2] row_mask:0xf bank_mask:0xf
	v_add_f32_dpp v151, v76, v77 quad_perm:[1,0,3,2] row_mask:0xf bank_mask:0xf
	v_add_f32_dpp v102, v149, v148 quad_perm:[2,3,0,1] row_mask:0xf bank_mask:0xf
	s_nop 0
	v_add_f32_dpp v103, v151, v150 quad_perm:[2,3,0,1] row_mask:0xf bank_mask:0xf
	v_cndmask_b32_e64 v144, v88, v89, s[88:89]
	v_cndmask_b32_e64 v145, v90, v91, s[88:89]
	v_cndmask_b32_e64 v88, v144, v145, s[86:87]
	v_cndmask_b32_e64 v144, v92, v93, s[88:89]
	v_cndmask_b32_e64 v145, v94, v95, s[88:89]
	v_cndmask_b32_e64 v92, v144, v145, s[86:87]
	v_cndmask_b32_e64 v144, v96, v97, s[88:89]
	v_cndmask_b32_e64 v145, v98, v99, s[88:89]
	v_cndmask_b32_e64 v96, v144, v145, s[86:87]
	v_cndmask_b32_e64 v144, v100, v101, s[88:89]
	v_cndmask_b32_e64 v145, v102, v103, s[88:89]
	v_cndmask_b32_e64 v100, v144, v145, s[86:87]
	v_cndmask_b32_e64 v144, v88, v92, s[90:91]
	v_cndmask_b32_e64 v145, v92, v88, s[90:91]
	v_cndmask_b32_e64 v146, v96, v100, s[90:91]
	v_cndmask_b32_e64 v147, v100, v96, s[90:91]
	s_nop 1
	v_add_f32_dpp v88, v145, v144 row_shl:4 row_mask:0xf bank_mask:0x5
	v_add_f32_dpp v88, v145, v144 row_shr:4 row_mask:0xf bank_mask:0xa
	v_add_f32_dpp v96, v147, v146 row_shl:4 row_mask:0xf bank_mask:0x5
	v_add_f32_dpp v96, v147, v146 row_shr:4 row_mask:0xf bank_mask:0xa
	s_waitcnt lgkmcnt(0)
	v_add_f32_e32 v136, v136, v88
	v_add_f32_e32 v137, v137, v96
	ds_write_b32 v117, v136
	ds_write_b32 v117, v137 offset:32
	s_add_u32 s100, s100, 1
	s_cmp_lt_u32 s100, 128
	s_cbranch_scc1 .Lpg0_uloop
	s_waitcnt vmcnt(0) lgkmcnt(0)
	s_mov_b32 s2, 0
